# chunk scan: loader wave + shared 4-buffer ring, y stores as the compiler wrote them
# baseline (speedup 1.0000x reference)
.LBB0_982:
	s_and_b64 s[12:13], s[8:9], exec
	s_cselect_b32 s11, 64, 8
	s_lshl_b32 s12, s6, 11
	s_addk_i32 s12, 0x2000
	s_lshl_b32 s13, s6, 8
	s_and_b64 s[8:9], s[8:9], exec
	s_cselect_b32 s12, s12, s13
	s_ashr_i32 s13, s12, 5
	s_add_i32 s14, s11, -1
	s_cmp_eq_u32 s16, 0
	s_cselect_b64 s[92:93], -1, 0
	v_mov_b32_e32 v35, v234
	s_and_b64 s[8:9], s[92:93], exec
	s_mov_b32 s4, s6
	s_cselect_b32 s8, 0, s14
	v_ashrrev_i32_e32 v0, 3, v35
	v_writelane_b32 v255, s4, 62
	v_sub_u32_e32 v34, 31, v0
	s_add_i32 s8, s13, s8
	v_writelane_b32 v255, s5, 63
	v_cndmask_b32_e64 v38, v34, v0, s[92:93]
	s_lshl_b32 s9, s8, 5
	s_lshl_b32 s14, s16, 8
	s_lshl_b32 s16, s16, 9
	v_readlane_b32 s4, v255, 13
	v_add_u32_e32 v38, s9, v38
	s_add_u32 s94, s4, s16
	v_readlane_b32 s4, v255, 14
	v_lshlrev_b32_e32 v42, 4, v35
	v_ashrrev_i32_e32 v39, 31, v38
	s_addc_u32 s95, s4, 0
	v_and_b32_e32 v0, 0x70, v42
	v_lshlrev_b64 v[38:39], 4, v[38:39]
	v_lshl_add_u64 v[36:37], s[94:95], 0, v[0:1]
	v_or_b32_e32 v0, s26, v38
	s_sub_u32 s96, 0, s14
	v_mad_u64_u32 v[40:41], s[14:15], v0, s33, v[36:37]
	v_mad_i32_i24 v41, v39, s33, v41
	s_mov_b32 m0, s22
	s_nop 0
	s_nop 0
	s_mov_b64 s[4:5], 0x80
	v_lshl_add_u64 v[38:39], v[40:41], 0, s[4:5]
	s_mov_b32 m0, s19
	s_nop 0
	s_nop 0
	s_mov_b32 s20, s19
	s_mov_b64 s[18:19], 0x100
	v_lshl_add_u64 v[38:39], v[40:41], 0, s[18:19]
	s_mov_b64 s[24:25], 0x180
	v_readlane_b32 s6, v255, 4
	s_mov_b32 m0, s6
	s_nop 0
	s_nop 0
	v_lshl_add_u64 v[38:39], v[40:41], 0, s[24:25]
	v_readlane_b32 s6, v255, 5
	s_mov_b32 m0, s6
	s_nop 0
	s_nop 0
	v_subrev_co_u32_e32 v38, vcc, s16, v40
	s_mov_b64 s[6:7], 0x400
	s_nop 0
	v_subbrev_co_u32_e32 v39, vcc, 0, v41, vcc
	v_add_u32_e32 v0, 64, v35
	v_lshl_add_u64 v[38:39], v[38:39], 0, s[6:7]
	v_ashrrev_i32_e32 v0, 3, v0
	v_readlane_b32 s15, v255, 9
	s_mov_b32 m0, s15
	s_nop 0
	s_nop 0
	v_sub_u32_e32 v38, 31, v0
	v_cndmask_b32_e64 v0, v38, v0, s[92:93]
	v_add_u32_e32 v38, s9, v0
	v_ashrrev_i32_e32 v39, 31, v38
	v_lshlrev_b64 v[38:39], 4, v[38:39]
	v_or_b32_e32 v0, s26, v38
	v_mad_u64_u32 v[40:41], s[14:15], v0, s33, v[36:37]
	v_mad_i32_i24 v41, v39, s33, v41
	v_readlane_b32 s15, v255, 2
	s_mov_b32 m0, s15
	s_nop 0
	s_nop 0
	v_lshl_add_u64 v[38:39], v[40:41], 0, s[4:5]
	v_readlane_b32 s15, v255, 3
	s_mov_b32 m0, s15
	s_nop 0
	s_nop 0
	v_lshl_add_u64 v[38:39], v[40:41], 0, s[18:19]
	v_readlane_b32 s15, v255, 41
	s_mov_b32 m0, s15
	s_nop 0
	s_nop 0
	v_lshl_add_u64 v[38:39], v[40:41], 0, s[24:25]
	v_readlane_b32 s15, v255, 42
	s_mov_b32 m0, s15
	s_nop 0
	s_nop 0
	v_subrev_co_u32_e32 v38, vcc, s16, v40
	v_add_u32_e32 v0, 0x80, v35
	s_nop 0
	v_subbrev_co_u32_e32 v39, vcc, 0, v41, vcc
	v_lshl_add_u64 v[38:39], v[38:39], 0, s[6:7]
	v_ashrrev_i32_e32 v0, 3, v0
	v_readlane_b32 s15, v255, 43
	s_mov_b32 m0, s15
	s_nop 0
	s_nop 0
	v_sub_u32_e32 v38, 31, v0
	v_cndmask_b32_e64 v0, v38, v0, s[92:93]
	v_add_u32_e32 v38, s9, v0
	v_ashrrev_i32_e32 v39, 31, v38
	v_lshlrev_b64 v[38:39], 4, v[38:39]
	v_or_b32_e32 v0, s26, v38
	v_mad_u64_u32 v[40:41], s[14:15], v0, s33, v[36:37]
	v_mad_i32_i24 v41, v39, s33, v41
	v_readlane_b32 s15, v255, 44
	s_mov_b32 m0, s15
	s_nop 0
	s_nop 0
	v_lshl_add_u64 v[38:39], v[40:41], 0, s[4:5]
	v_readlane_b32 s15, v255, 45
	s_mov_b32 m0, s15
	s_nop 0
	s_nop 0
	v_lshl_add_u64 v[38:39], v[40:41], 0, s[18:19]
	v_readlane_b32 s15, v255, 46
	s_mov_b32 m0, s15
	s_nop 0
	s_nop 0
	v_lshl_add_u64 v[38:39], v[40:41], 0, s[24:25]
	v_add_u32_e32 v0, 0xc0, v35
	v_readlane_b32 s15, v255, 47
	s_mov_b32 m0, s15
	s_nop 0
	s_nop 0
	v_subrev_co_u32_e32 v38, vcc, s16, v40
	v_ashrrev_i32_e32 v0, 3, v0
	v_lshlrev_b32_e32 v34, 3, v35
	v_subbrev_co_u32_e32 v39, vcc, 0, v41, vcc
	v_sub_u32_e32 v35, 31, v0
	v_lshl_add_u64 v[38:39], v[38:39], 0, s[6:7]
	v_cndmask_b32_e64 v0, v35, v0, s[92:93]
	v_readlane_b32 s15, v255, 48
	s_mov_b32 m0, s15
	s_nop 0
	s_nop 0
	v_add_u32_e32 v38, s9, v0
	v_ashrrev_i32_e32 v39, 31, v38
	v_lshlrev_b64 v[38:39], 4, v[38:39]
	v_or_b32_e32 v0, s26, v38
	v_mad_u64_u32 v[36:37], s[14:15], v0, s33, v[36:37]
	v_mad_i32_i24 v37, v39, s33, v37
	v_readlane_b32 s14, v255, 49
	s_mov_b32 m0, s14
	s_nop 0
	s_nop 0
	v_lshl_add_u64 v[38:39], v[36:37], 0, s[4:5]
	v_readlane_b32 s4, v255, 50
	s_mov_b32 m0, s4
	s_nop 0
	s_nop 0
	v_lshl_add_u64 v[38:39], v[36:37], 0, s[18:19]
	v_readlane_b32 s4, v255, 51
	s_mov_b32 m0, s4
	s_nop 0
	s_nop 0
	v_lshl_add_u64 v[38:39], v[36:37], 0, s[24:25]
	v_subrev_co_u32_e32 v36, vcc, s16, v36
	v_readlane_b32 s4, v255, 52
	s_mov_b32 m0, s4
	s_nop 0
	s_nop 0
	s_nop 0
	v_subbrev_co_u32_e32 v37, vcc, 0, v37, vcc
	v_lshl_add_u64 v[36:37], v[36:37], 0, s[6:7]
	v_readlane_b32 s4, v255, 53
	s_mov_b32 m0, s4
	s_nop 0
	s_nop 0
	s_subb_u32 s97, 0, 0
	s_ashr_i32 s9, s8, 31
	v_readlane_b32 s24, v255, 59
	s_lshl_b64 s[8:9], s[8:9], 5
	s_lshl_b32 s16, s24, 4
	s_or_b32 s8, s8, s16
	s_or_b32 s8, s8, s26
	s_lshl_b64 s[14:15], s[8:9], 11
	v_readlane_b32 s4, v255, 6
	s_add_u32 s14, s4, s14
	v_readlane_b32 s4, v255, 0
	s_addc_u32 s15, s4, s15
	v_ashrrev_i32_e32 v35, 31, v34
	s_lshl_b64 s[8:9], s[8:9], 8
	v_lshl_add_u64 v[34:35], v[34:35], 1, s[14:15]
	v_readlane_b32 s4, v255, 10
	s_mov_b32 m0, s4
	s_nop 0
	s_nop 0
	s_add_u32 s8, s27, s8
	v_lshl_add_u64 v[34:35], v[34:35], 0, s[6:7]
	v_readlane_b32 s4, v255, 54
	s_mov_b32 m0, s4
	s_nop 0
	s_nop 0
	s_addc_u32 s9, s23, s9
	v_and_b32_e32 v0, 0xf0, v42
	v_lshl_add_u64 v[34:35], s[8:9], 0, v[0:1]
	v_readlane_b32 s4, v255, 11
	s_mov_b32 m0, s4
	s_nop 0
	s_nop 0
	s_lshl_b32 s14, s10, 6
	s_lshl_b32 s8, s24, 26
	v_readlane_b32 s4, v255, 15
	s_add_u32 s8, s4, s8
	v_readlane_b32 s4, v255, 16
	s_addc_u32 s9, s4, 0
	s_lshl_b32 s15, s26, 8
	s_add_u32 s8, s8, s15
	s_addc_u32 s9, s9, 0
	s_lshl_b32 s10, s10, 7
	s_add_u32 s8, s8, s10
	s_addc_u32 s9, s9, 0
	v_mov_b32_e32 v155, v1
	s_mov_b32 s21, 0
	s_mov_b32 s19, s20
	v_add_u32_e32 v157, s14, v176
	v_lshl_add_u64 v[158:159], s[8:9], 0, v[154:155]
	v_cndmask_b32_e64 v155, v177, v152, s[92:93]
	v_cndmask_b32_e64 v197, v178, v161, s[92:93]
	v_cndmask_b32_e64 v198, v179, v162, s[92:93]
	v_cndmask_b32_e64 v199, v180, v163, s[92:93]
	v_cndmask_b32_e64 v200, v181, v164, s[92:93]
	v_cndmask_b32_e64 v201, v182, v165, s[92:93]
	v_cndmask_b32_e64 v202, v183, v166, s[92:93]
	v_cndmask_b32_e64 v203, v184, v167, s[92:93]
	v_cndmask_b32_e64 v204, v185, v168, s[92:93]
	v_cndmask_b32_e64 v205, v186, v169, s[92:93]
	v_cndmask_b32_e64 v206, v187, v170, s[92:93]
	v_cndmask_b32_e64 v207, v188, v171, s[92:93]
	v_cndmask_b32_e64 v208, v189, v172, s[92:93]
	v_cndmask_b32_e64 v209, v190, v173, s[92:93]
	v_cndmask_b32_e64 v210, v191, v174, s[92:93]
	v_cndmask_b32_e64 v211, v192, v175, s[92:93]
	v_add_u32_e32 v212, s14, v193
	s_or_b32 s16, s26, s16
	s_add_i32 s20, s11, -3
	v_readlane_b32 s25, v255, 60
	s_waitcnt vmcnt(0)
	s_branch .LBB0_984
.LBB0_983:
	ds_read_b128 v[112:115], v194 offset:31744
	ds_read_b128 v[66:69], v194 offset:23552
	ds_read_b128 v[70:73], v194 offset:23584
	ds_read_b128 v[116:119], v194 offset:31776
	s_nop 5
	v_pk_add_f32 v[32:33], v[64:65], v[32:33]
	v_pk_add_f32 v[142:143], v[62:63], v[30:31]
	s_waitcnt lgkmcnt(2)
	v_mfma_f32_32x32x16_bf16 v[76:91], v[112:115], v[66:69], 0
	v_add_f32_e64 v218, v60, v28
	v_add_f32_e64 v219, v61, v29
	v_add_f32_e64 v20, v52, v20
	v_add_f32_e64 v21, v53, v21
	v_add_f32_e64 v18, v50, v18
	v_add_f32_e64 v19, v51, v19
	v_pk_add_f32 v[26:27], v[58:59], v[26:27]
	v_pk_add_f32 v[24:25], v[56:57], v[24:25]
	v_pk_add_f32 v[22:23], v[54:55], v[22:23]
	v_pk_add_f32 v[16:17], v[48:49], v[16:17]
	s_waitcnt lgkmcnt(0)
	v_mfma_f32_32x32x16_bf16 v[76:91], v[116:119], v[70:73], v[76:91]
	ds_read_b128 v[134:137], v194 offset:31808
	ds_read_b128 v[66:69], v194 offset:23616
	ds_read_b128 v[138:141], v194 offset:31840
	ds_read_b128 v[70:73], v194 offset:23648
	v_add_f32_e64 v14, v46, v14
	v_add_f32_e64 v15, v47, v15
	v_pk_add_f32 v[12:13], v[44:45], v[12:13]
	v_pk_add_f32 v[10:11], v[42:43], v[10:11]
	v_pk_add_f32 v[8:9], v[40:41], v[8:9]
	v_pk_add_f32 v[6:7], v[38:39], v[6:7]
	v_pk_add_f32 v[4:5], v[36:37], v[4:5]
	s_waitcnt lgkmcnt(2)
	v_mfma_f32_32x32x16_bf16 v[76:91], v[134:137], v[66:69], v[76:91]
	ds_read_b128 v[66:69], v194 offset:27648
	ds_read_b128 v[146:149], v194 offset:35840
	ds_read_b128 v[28:31], v194 offset:27680
	ds_read_b128 v[214:217], v194 offset:35872
	ds_read_b128 v[50:53], v194 offset:27712
	ds_read_b128 v[56:59], v194 offset:35904
	v_pk_add_f32 v[2:3], v[34:35], v[2:3]
	v_pk_mul_f32 v[22:23], v[126:127], v[22:23]
	s_waitcnt lgkmcnt(6)
	v_mfma_f32_32x32x16_bf16 v[76:91], v[138:141], v[70:73], v[76:91]
	v_mul_f32_e64 v24, v128, v24
	v_mul_f32_e64 v25, v129, v25
	v_mul_f32_e64 v26, v122, v26
	v_mul_f32_e64 v27, v123, v27
	ds_read_b128 v[120:123], v194 offset:27744
	ds_read_b128 v[126:129], v194 offset:35936
	v_pk_mul_f32 v[18:19], v[130:131], v[18:19]
	v_pk_mul_f32 v[20:21], v[132:133], v[20:21]
	v_pk_mul_f32 v[32:33], v[110:111], v[32:33]
	v_pk_mul_f32 v[6:7], v[96:97], v[6:7]
	s_waitcnt lgkmcnt(6)
	v_mfma_f32_32x32x16_bf16 v[60:75], v[66:69], v[146:149], 0
	v_cndmask_b32_e64 v0, 0, v76, s[0:1]
	v_cndmask_b32_e64 v34, 0, v77, s[2:3]
	v_cndmask_b32_e64 v35, 0, v78, s[34:35]
	v_cndmask_b32_e64 v36, 0, v79, s[36:37]
	v_cndmask_b32_e64 v37, 0, v80, s[38:39]
	v_cndmask_b32_e64 v38, 0, v81, s[40:41]
	v_cndmask_b32_e64 v39, 0, v82, s[42:43]
	s_waitcnt lgkmcnt(4)
	v_mfma_f32_32x32x16_bf16 v[60:75], v[28:31], v[214:217], v[60:75]
	v_cndmask_b32_e64 v76, 0, v83, s[44:45]
	v_cvt_pk_bf16_f32 v34, v0, v34
	v_cvt_pk_bf16_f32 v35, v35, v36
	v_cvt_pk_bf16_f32 v36, v37, v38
	v_cvt_pk_bf16_f32 v37, v39, v76
	v_cndmask_b32_e64 v77, 0, v84, s[46:47]
	v_cndmask_b32_e64 v78, 0, v85, s[48:49]
	s_waitcnt lgkmcnt(2)
	v_mfma_f32_32x32x16_bf16 v[60:75], v[50:53], v[56:59], v[60:75]
	v_mul_f32_e64 v28, v124, v218
	v_mul_f32_e64 v29, v125, v219
	v_mul_f32_e64 v30, v108, v142
	v_mul_f32_e64 v31, v109, v143
	v_mul_f32_e64 v8, v98, v8
	v_mul_f32_e64 v9, v99, v9
	v_pk_mul_f32 v[14:15], v[92:93], v[14:15]
	v_cndmask_b32_e64 v92, 0, v90, s[58:59]
	v_cndmask_b32_e64 v93, 0, v91, s[60:61]
	v_cvt_pk_bf16_f32 v96, v77, v78
	v_mfma_f32_32x32x16_bf16 v[40:55], v[112:115], v[146:149], 0
	v_cvt_pk_bf16_f32 v99, v92, v93
	v_mul_f32_e64 v2, v100, v2
	v_mul_f32_e64 v3, v101, v3
	v_add_u32_e32 v100, 0x5800, v195
	v_cvt_pk_bf16_f32 v146, v18, v19
	v_cvt_pk_bf16_f32 v147, v20, v21
	v_cvt_pk_bf16_f32 v148, v22, v23
	v_cvt_pk_bf16_f32 v149, v24, v25
	v_mfma_f32_32x32x16_bf16 v[40:55], v[116:119], v[214:217], v[40:55]
	v_cvt_pk_bf16_f32 v214, v26, v27
	v_cvt_pk_bf16_f32 v215, v28, v29
	v_cvt_pk_bf16_f32 v216, v30, v31
	v_cvt_pk_bf16_f32 v217, v32, v33
	v_mul_f32_e64 v16, v94, v16
	v_mul_f32_e64 v17, v95, v17
	v_pk_mul_f32 v[4:5], v[102:103], v[4:5]
	v_cvt_pk_bf16_f32 v228, v2, v3
	v_mfma_f32_32x32x16_bf16 v[40:55], v[134:137], v[56:59], v[40:55]
	v_cndmask_b32_e64 v56, 0, v86, s[50:51]
	v_cndmask_b32_e64 v57, 0, v87, s[52:53]
	v_cndmask_b32_e64 v58, 0, v88, s[54:55]
	v_cndmask_b32_e64 v59, 0, v89, s[56:57]
	v_cvt_pk_bf16_f32 v97, v56, v57
	v_cvt_pk_bf16_f32 v98, v58, v59
	v_cvt_pk_bf16_f32 v229, v4, v5
	s_waitcnt lgkmcnt(0)
	v_mfma_f32_32x32x16_bf16 v[60:75], v[120:123], v[126:129], v[60:75]
	v_cvt_pk_bf16_f32 v230, v6, v7
	v_cvt_pk_bf16_f32 v231, v8, v9
	v_mul_f32_e64 v10, v104, v10
	v_mul_f32_e64 v11, v105, v11
	v_mul_f32_e64 v12, v106, v12
	v_mul_f32_e64 v13, v107, v13
	v_cvt_pk_bf16_f32 v242, v10, v11
	v_cvt_pk_bf16_f32 v243, v12, v13
	v_cvt_pk_bf16_f32 v244, v14, v15
	v_mfma_f32_32x32x16_bf16 v[40:55], v[138:141], v[126:129], v[40:55]
	ds_read_b64_tr_b16 v[136:137], v212 offset:0x4000
	ds_read_b64_tr_b16 v[138:139], v212 offset:0x4000+1024
	ds_read_b64_tr_b16 v[128:129], v212 offset:0x4000+2048
	ds_read_b64_tr_b16 v[130:131], v212 offset:0x4000+3072
	ds_read_b64_tr_b16 v[120:121], v193 offset:0x1000
	ds_read_b64_tr_b16 v[122:123], v193 offset:0x1000+1024
	ds_read_b64_tr_b16 v[116:117], v193 offset:0x1000+2048
	ds_read_b64_tr_b16 v[118:119], v193 offset:0x1000+3072
	ds_read_b64_tr_b16 v[112:113], v193 offset:0x1000+64
	ds_read_b64_tr_b16 v[114:115], v193 offset:0x1000+64+1024
	ds_read_b64_tr_b16 v[108:109], v193 offset:0x1000+64+2048
	ds_read_b64_tr_b16 v[110:111], v193 offset:0x1000+64+3072
	ds_read_b64_tr_b16 v[140:141], v193 offset:0x2000
	ds_read_b64_tr_b16 v[142:143], v193 offset:0x2000+1024
	ds_read_b64_tr_b16 v[132:133], v193 offset:0x2000+2048
	ds_read_b64_tr_b16 v[134:135], v193 offset:0x2000+3072
	ds_read_b64_tr_b16 v[56:57], v193 offset:0x2000+64
	ds_read_b64_tr_b16 v[58:59], v193 offset:0x2000+64+1024
	ds_read_b64_tr_b16 v[124:125], v193 offset:0x2000+64+2048
	ds_read_b64_tr_b16 v[126:127], v193 offset:0x2000+64+3072
	s_waitcnt lgkmcnt(0)
	v_cvt_pk_bf16_f32 v245, v16, v17
	s_nop 0
	v_cndmask_b32_e64 v60, v60, 0, s[62:63]
	v_cndmask_b32_e64 v61, 0, v61, s[0:1]
	v_cvt_pk_bf16_f32 v60, v60, v61
	v_cndmask_b32_e64 v72, v72, 0, s[84:85]
	s_xor_b32 s14, s21, 0x7fffffe
	v_mfma_f32_32x32x16_bf16 v[76:91], v[34:37], v[136:139], 0
	ds_read2_b64 v[34:37], v100 offset0:128 offset1:130
	s_nop 2
	v_cndmask_b32_e64 v0, v40, 0, s[62:63]
	v_cndmask_b32_e64 v92, 0, v41, s[0:1]
	ds_read2_b64 v[38:41], v100 offset0:132 offset1:134
	v_cndmask_b32_e64 v213, v50, 0, s[80:81]
	v_add_u32_e32 v50, 0xa800, v196
	v_cndmask_b32_e64 v42, v42, 0, s[64:65]
	v_mfma_f32_32x32x16_bf16 v[76:91], v[96:99], v[128:131], v[76:91]
	ds_read2_b64 v[96:99], v100 offset0:140 offset1:142
	v_cndmask_b32_e64 v43, v43, 0, s[66:67]
	v_cndmask_b32_e64 v44, v44, 0, s[68:69]
	v_cndmask_b32_e64 v45, v45, 0, s[70:71]
	v_cndmask_b32_e64 v218, v51, 0, s[82:83]
	v_cndmask_b32_e64 v219, v52, 0, s[84:85]
	v_cndmask_b32_e64 v237, v53, 0, s[86:87]
	s_waitcnt lgkmcnt(2)
	v_mfma_f32_32x32x16_bf16 v[76:91], v[34:37], v[146:149], v[76:91]
	v_cvt_pk_bf16_f32 v34, v0, v92
	ds_read2_b64 v[92:95], v100 offset0:136 offset1:138
	v_cndmask_b32_e64 v37, v46, 0, s[72:73]
	v_cndmask_b32_e64 v46, v47, 0, s[74:75]
	v_cvt_pk_bf16_f32 v35, v42, v43
	v_cvt_pk_bf16_f32 v36, v44, v45
	v_cvt_pk_bf16_f32 v37, v37, v46
	s_waitcnt lgkmcnt(2)
	v_mfma_f32_32x32x16_bf16 v[76:91], v[38:41], v[214:217], v[76:91]
	v_cndmask_b32_e64 v0, v48, 0, s[76:77]
	v_cndmask_b32_e64 v145, v49, 0, s[78:79]
	v_cndmask_b32_e64 v54, v54, 0, s[88:89]
	v_cndmask_b32_e64 v55, v55, 0, s[90:91]
	s_add_i32 s21, s14, s11
	s_and_b64 s[14:15], s[92:93], exec
	s_cselect_b32 s10, s10, s21
	s_waitcnt lgkmcnt(0)
	v_mfma_f32_32x32x16_bf16 v[76:91], v[92:95], v[228:231], v[76:91]
	ds_read2_b64 v[92:95], v50 offset0:128 offset1:130
	ds_read2_b64 v[50:53], v50 offset0:132 offset1:134
	s_lshl_b32 s10, s10, 5
	s_add_i32 s10, s10, s12
	s_add_i32 s20, s20, -2
	s_and_b64 vcc, exec, s[8:9]
	s_mov_b32 s21, s18
	v_mfma_f32_32x32x16_bf16 v[76:91], v[96:99], v[242:245], v[76:91]
	v_mfma_f32_32x32x16_bf16 v[34:49], v[34:37], v[136:139], 0
	s_nop 10
	v_cvt_pk_bf16_f32 v76, v76, v77
	v_cvt_pk_bf16_f32 v77, v78, v79
	v_cvt_pk_bf16_f32 v78, v80, v81
	v_cvt_pk_bf16_f32 v79, v82, v83
	v_cvt_pk_bf16_f32 v80, v88, v89
	v_cvt_pk_bf16_f32 v81, v90, v91
	s_waitcnt lgkmcnt(1)
	v_mfma_f32_32x32x16_bf16 v[92:107], v[92:95], v[76:79], 0
	v_cvt_pk_bf16_f32 v78, v84, v85
	v_cvt_pk_bf16_f32 v79, v86, v87
	v_cvt_pk_bf16_f32 v76, v0, v145
	v_cvt_pk_bf16_f32 v77, v213, v218
	v_add_u32_e32 v0, 0x8800, v195
	s_waitcnt lgkmcnt(0)
	v_mfma_f32_32x32x16_bf16 v[92:107], v[50:53], v[78:81], v[92:107]
	v_cvt_pk_bf16_f32 v78, v219, v237
	v_cvt_pk_bf16_f32 v79, v54, v55
	ds_read2_b64 v[50:53], v0 offset0:128 offset1:130
	s_nop 0
	v_mfma_f32_32x32x16_bf16 v[34:49], v[76:79], v[128:131], v[34:49]
	ds_read2_b64 v[76:79], v0 offset0:132 offset1:134
	s_nop 5
	v_cvt_pk_bf16_f32 v86, v92, v93
	v_cvt_pk_bf16_f32 v87, v94, v95
	v_cvt_pk_bf16_f32 v88, v96, v97
	v_cvt_pk_bf16_f32 v89, v98, v99
	v_cvt_pk_bf16_f32 v82, v100, v101
	v_cvt_pk_bf16_f32 v83, v102, v103
	s_waitcnt lgkmcnt(1)
	v_mfma_f32_32x32x16_bf16 v[34:49], v[50:53], v[146:149], v[34:49]
	ds_read2_b64 v[52:55], v0 offset0:136 offset1:138
	v_cndmask_b32_e64 v50, v68, 0, s[76:77]
	v_cndmask_b32_e64 v51, v69, 0, s[78:79]
	v_cvt_pk_bf16_f32 v50, v50, v51
	v_cndmask_b32_e64 v51, v70, 0, s[80:81]
	v_cndmask_b32_e64 v68, v71, 0, s[82:83]
	v_cvt_pk_bf16_f32 v51, v51, v68
	s_waitcnt lgkmcnt(1)
	v_mfma_f32_32x32x16_bf16 v[34:49], v[76:79], v[214:217], v[34:49]
	ds_read2_b64 v[68:71], v0 offset0:140 offset1:142
	v_cndmask_b32_e64 v0, v62, 0, s[64:65]
	v_cvt_pk_bf16_f32 v84, v104, v105
	v_cvt_pk_bf16_f32 v85, v106, v107
	s_waitcnt lgkmcnt(1)
	v_mfma_f32_32x32x16_bf16 v[34:49], v[52:55], v[228:231], v[34:49]
	v_cndmask_b32_e64 v52, v63, 0, s[66:67]
	v_cndmask_b32_e64 v53, v64, 0, s[68:69]
	v_cndmask_b32_e64 v54, v65, 0, s[70:71]
	v_cndmask_b32_e64 v55, v66, 0, s[72:73]
	v_cndmask_b32_e64 v63, v67, 0, s[74:75]
	v_cvt_pk_bf16_f32 v61, v0, v52
	v_cvt_pk_bf16_f32 v62, v53, v54
	s_waitcnt lgkmcnt(0)
	v_mfma_f32_32x32x16_bf16 v[34:49], v[68:71], v[242:245], v[34:49]
	v_cvt_pk_bf16_f32 v63, v55, v63
	v_cndmask_b32_e64 v0, v73, 0, s[86:87]
	v_cvt_pk_bf16_f32 v52, v72, v0
	v_cndmask_b32_e64 v0, v74, 0, s[88:89]
	v_cndmask_b32_e64 v53, v75, 0, s[90:91]
	v_cvt_pk_bf16_f32 v53, v0, v53
	v_add_u32_e32 v54, s10, v155
	v_mfma_f32_32x32x16_bf16 v[34:49], v[60:63], v[86:89], v[34:49]
	v_ashrrev_i32_e32 v55, 31, v54
	v_lshlrev_b64 v[54:55], 12, v[54:55]
	v_lshl_add_u64 v[54:55], v[158:159], 0, v[54:55]
	v_mfma_f32_32x32x16_bf16 v[34:49], v[50:53], v[82:85], v[34:49]
	v_add_u32_e32 v50, s10, v197
	v_ashrrev_i32_e32 v51, 31, v50
	v_lshlrev_b64 v[50:51], 12, v[50:51]
	v_lshl_add_u64 v[50:51], v[158:159], 0, v[50:51]
	v_mfma_f32_32x32x16_bf16 v[66:81], v[140:143], v[136:139], 0
	s_nop 6
	global_store_dword v[54:55], v34, off
	v_add_u32_e32 v34, s10, v198
	global_store_dword v[50:51], v35, off
	v_ashrrev_i32_e32 v35, 31, v34
	v_lshlrev_b64 v[34:35], 12, v[34:35]
	v_lshl_add_u64 v[34:35], v[158:159], 0, v[34:35]
	global_store_dword v[34:35], v36, off
	v_add_u32_e32 v34, s10, v199
	v_ashrrev_i32_e32 v35, 31, v34
	v_lshlrev_b64 v[34:35], 12, v[34:35]
	v_lshl_add_u64 v[34:35], v[158:159], 0, v[34:35]
	global_store_dword v[34:35], v37, off
	v_add_u32_e32 v34, s10, v200
	v_ashrrev_i32_e32 v35, 31, v34
	v_lshlrev_b64 v[34:35], 12, v[34:35]
	v_lshl_add_u64 v[34:35], v[158:159], 0, v[34:35]
	global_store_dword v[34:35], v38, off
	v_add_u32_e32 v34, s10, v201
	v_ashrrev_i32_e32 v35, 31, v34
	v_lshlrev_b64 v[34:35], 12, v[34:35]
	v_lshl_add_u64 v[34:35], v[158:159], 0, v[34:35]
	global_store_dword v[34:35], v39, off
	v_add_u32_e32 v34, s10, v202
	v_ashrrev_i32_e32 v35, 31, v34
	v_lshlrev_b64 v[34:35], 12, v[34:35]
	v_lshl_add_u64 v[34:35], v[158:159], 0, v[34:35]
	global_store_dword v[34:35], v40, off
	v_add_u32_e32 v34, s10, v203
	v_ashrrev_i32_e32 v35, 31, v34
	v_lshlrev_b64 v[34:35], 12, v[34:35]
	v_lshl_add_u64 v[34:35], v[158:159], 0, v[34:35]
	global_store_dword v[34:35], v41, off
	v_add_u32_e32 v34, s10, v204
	v_ashrrev_i32_e32 v35, 31, v34
	v_lshlrev_b64 v[34:35], 12, v[34:35]
	v_lshl_add_u64 v[34:35], v[158:159], 0, v[34:35]
	global_store_dword v[34:35], v42, off
	v_add_u32_e32 v34, s10, v205
	v_ashrrev_i32_e32 v35, 31, v34
	v_lshlrev_b64 v[34:35], 12, v[34:35]
	v_lshl_add_u64 v[34:35], v[158:159], 0, v[34:35]
	global_store_dword v[34:35], v43, off
	v_add_u32_e32 v34, s10, v206
	v_ashrrev_i32_e32 v35, 31, v34
	v_lshlrev_b64 v[34:35], 12, v[34:35]
	v_lshl_add_u64 v[34:35], v[158:159], 0, v[34:35]
	global_store_dword v[34:35], v44, off
	v_add_u32_e32 v34, s10, v207
	v_ashrrev_i32_e32 v35, 31, v34
	v_lshlrev_b64 v[34:35], 12, v[34:35]
	v_lshl_add_u64 v[34:35], v[158:159], 0, v[34:35]
	global_store_dword v[34:35], v45, off
	v_add_u32_e32 v34, s10, v208
	v_ashrrev_i32_e32 v35, 31, v34
	v_lshlrev_b64 v[34:35], 12, v[34:35]
	v_lshl_add_u64 v[34:35], v[158:159], 0, v[34:35]
	global_store_dword v[34:35], v46, off
	v_add_u32_e32 v34, s10, v209
	v_ashrrev_i32_e32 v35, 31, v34
	v_mfma_f32_32x32x16_bf16 v[18:33], v[120:123], v[86:89], v[18:33]
	v_lshlrev_b64 v[34:35], 12, v[34:35]
	v_lshl_add_u64 v[34:35], v[158:159], 0, v[34:35]
	global_store_dword v[34:35], v47, off
	v_add_u32_e32 v34, s10, v210
	v_ashrrev_i32_e32 v35, 31, v34
	v_lshlrev_b64 v[34:35], 12, v[34:35]
	v_lshl_add_u64 v[34:35], v[158:159], 0, v[34:35]
	v_mfma_f32_32x32x16_bf16 v[50:65], v[56:59], v[136:139], 0
	global_store_dword v[34:35], v48, off
	v_add_u32_e32 v34, s10, v211
	v_ashrrev_i32_e32 v35, 31, v34
	v_lshlrev_b64 v[34:35], 12, v[34:35]
	v_lshl_add_u64 v[34:35], v[158:159], 0, v[34:35]
	global_store_dword v[34:35], v49, off
	ds_read_b128 v[34:37], v144 offset:46080
	ds_read_b128 v[38:41], v144 offset:46112
	ds_read_b128 v[42:45], v144 offset:46144
	ds_read_b128 v[46:49], v144 offset:46176
	v_mfma_f32_32x32x16_bf16 v[2:17], v[112:115], v[86:89], v[2:17]
	v_mfma_f32_32x32x16_bf16 v[66:81], v[132:135], v[128:131], v[66:81]
	v_mfma_f32_32x32x16_bf16 v[18:33], v[116:119], v[82:85], v[18:33]
	v_mfma_f32_32x32x16_bf16 v[50:65], v[124:127], v[128:131], v[50:65]
	s_nop 10
	v_add_f32_e64 v32, v80, v32
	v_add_f32_e64 v33, v81, v33
	v_add_f32_e64 v30, v78, v30
	v_add_f32_e64 v31, v79, v31
	v_add_f32_e64 v28, v76, v28
	v_add_f32_e64 v29, v77, v29
	v_pk_add_f32 v[26:27], v[74:75], v[26:27]
	v_pk_add_f32 v[24:25], v[72:73], v[24:25]
	v_pk_add_f32 v[22:23], v[70:71], v[22:23]
	v_pk_add_f32 v[20:21], v[68:69], v[20:21]
	v_mfma_f32_32x32x16_bf16 v[2:17], v[108:111], v[82:85], v[2:17]
	v_add_f32_e64 v18, v66, v18
	v_add_f32_e64 v19, v67, v19
	s_waitcnt lgkmcnt(3)
	v_mul_f32_e64 v20, v36, v20
	v_mul_f32_e64 v21, v37, v21
	v_pk_mul_f32 v[18:19], v[34:35], v[18:19]
	s_waitcnt lgkmcnt(2)
	v_pk_mul_f32 v[22:23], v[38:39], v[22:23]
	v_pk_mul_f32 v[24:25], v[40:41], v[24:25]
	s_waitcnt lgkmcnt(1)
	v_pk_mul_f32 v[26:27], v[42:43], v[26:27]
	v_pk_mul_f32 v[28:29], v[44:45], v[28:29]
	s_waitcnt lgkmcnt(0)
	v_pk_mul_f32 v[30:31], v[46:47], v[30:31]
	v_pk_mul_f32 v[32:33], v[48:49], v[32:33]
	ds_read_b128 v[34:37], v144 offset:46208
	ds_read_b128 v[38:41], v144 offset:46240
	ds_read_b128 v[42:45], v144 offset:46272
	ds_read_b128 v[46:49], v144 offset:46304
	v_pk_add_f32 v[16:17], v[64:65], v[16:17]
	v_pk_add_f32 v[14:15], v[62:63], v[14:15]
	v_pk_add_f32 v[12:13], v[60:61], v[12:13]
	v_pk_add_f32 v[10:11], v[58:59], v[10:11]
	v_pk_add_f32 v[8:9], v[56:57], v[8:9]
	v_pk_add_f32 v[6:7], v[54:55], v[6:7]
	v_pk_add_f32 v[4:5], v[52:53], v[4:5]
	v_pk_add_f32 v[2:3], v[50:51], v[2:3]
	s_waitcnt lgkmcnt(3)
	v_pk_mul_f32 v[4:5], v[36:37], v[4:5]
	v_pk_mul_f32 v[2:3], v[34:35], v[2:3]
	s_waitcnt lgkmcnt(2)
	v_pk_mul_f32 v[6:7], v[38:39], v[6:7]
	v_pk_mul_f32 v[8:9], v[40:41], v[8:9]
	s_waitcnt lgkmcnt(1)
	v_pk_mul_f32 v[10:11], v[42:43], v[10:11]
	v_pk_mul_f32 v[12:13], v[44:45], v[12:13]
	s_waitcnt lgkmcnt(0)
	v_pk_mul_f32 v[14:15], v[46:47], v[14:15]
	v_pk_mul_f32 v[16:17], v[48:49], v[16:17]
	v_add_u32_e32 v157, s99, v157
	v_add_u32_e32 v176, s99, v176
	v_add_u32_e32 v193, s99, v193
	v_add_u32_e32 v194, s99, v194
	v_add_u32_e32 v195, s99, v195
	v_add_u32_e32 v196, s99, v196
	v_add_u32_e32 v212, s99, v212
	s_add_i32 s22, s22, s99
	s_sub_i32 s99, 0, s99
	s_cbranch_vccnz .LBB0_992

.LBB0_989:
	ds_read_b128 v[66:69], v194 offset:8192
	ds_read_b128 v[34:37], v194
	ds_read_b128 v[38:41], v194 offset:32
	ds_read_b128 v[82:85], v194 offset:8224
	v_cvt_pk_bf16_f32 v214, v18, v19
	v_cvt_pk_bf16_f32 v215, v20, v21
	s_waitcnt lgkmcnt(2)
	v_mfma_f32_32x32x16_bf16 v[50:65], v[66:69], v[34:37], 0
	v_cvt_pk_bf16_f32 v216, v22, v23
	v_cvt_pk_bf16_f32 v217, v24, v25
	v_cvt_pk_bf16_f32 v228, v26, v27
	v_cvt_pk_bf16_f32 v229, v28, v29
	v_cvt_pk_bf16_f32 v230, v30, v31
	v_cvt_pk_bf16_f32 v231, v32, v33
	v_add_u32_e32 v106, 0x5000, v196
	s_waitcnt lgkmcnt(0)
	v_mfma_f32_32x32x16_bf16 v[50:65], v[82:85], v[38:41], v[50:65]
	ds_read_b128 v[86:89], v194 offset:8256
	ds_read_b128 v[34:37], v194 offset:64
	ds_read_b128 v[90:93], v194 offset:8288
	ds_read_b128 v[38:41], v194 offset:96
	s_add_i32 s14, s20, 2
	s_and_b64 s[8:9], s[92:93], exec
	s_cselect_b32 s8, s21, s14
	s_lshl_b32 s8, s8, 5
	s_add_i32 s8, s8, s12
	s_add_i32 s18, s21, 2
	s_waitcnt lgkmcnt(2)
	v_mfma_f32_32x32x16_bf16 v[50:65], v[86:89], v[34:37], v[50:65]
	ds_read_b128 v[34:37], v194 offset:4096
	ds_read_b128 v[70:73], v194 offset:12288
	ds_read_b128 v[74:77], v194 offset:4128
	ds_read_b128 v[94:97], v194 offset:12320
	s_cmp_ge_u32 s18, s11
	s_waitcnt lgkmcnt(4)
	v_mfma_f32_32x32x16_bf16 v[50:65], v[90:93], v[38:41], v[50:65]
	s_waitcnt lgkmcnt(2)
	v_mfma_f32_32x32x16_bf16 v[34:49], v[34:37], v[70:73], 0
	s_nop 9
	v_cndmask_b32_e64 v0, 0, v50, s[0:1]
	v_cndmask_b32_e64 v50, 0, v51, s[2:3]
	v_cndmask_b32_e64 v51, 0, v52, s[34:35]
	v_cndmask_b32_e64 v52, 0, v53, s[36:37]
	v_cndmask_b32_e64 v53, 0, v54, s[38:39]
	v_cndmask_b32_e64 v57, 0, v57, s[44:45]
	v_cvt_pk_bf16_f32 v54, v0, v50
	s_waitcnt lgkmcnt(0)
	v_mfma_f32_32x32x16_bf16 v[34:49], v[74:77], v[94:97], v[34:49]
	ds_read_b128 v[74:77], v194 offset:4160
	ds_read_b128 v[98:101], v194 offset:12352
	ds_read_b128 v[78:81], v194 offset:4192
	ds_read_b128 v[102:105], v194 offset:12384
	v_cndmask_b32_e64 v58, 0, v58, s[46:47]
	v_cndmask_b32_e64 v59, 0, v59, s[48:49]
	v_cndmask_b32_e64 v60, 0, v60, s[50:51]
	v_cndmask_b32_e64 v61, 0, v61, s[52:53]
	v_cndmask_b32_e64 v62, 0, v62, s[54:55]
	v_cndmask_b32_e64 v63, 0, v63, s[56:57]
	s_waitcnt lgkmcnt(2)
	v_mfma_f32_32x32x16_bf16 v[34:49], v[74:77], v[98:101], v[34:49]
	v_cndmask_b32_e64 v64, 0, v64, s[58:59]
	v_cndmask_b32_e64 v0, 0, v65, s[60:61]
	v_cvt_pk_bf16_f32 v58, v58, v59
	v_cvt_pk_bf16_f32 v59, v60, v61
	v_cvt_pk_bf16_f32 v60, v62, v63
	v_cvt_pk_bf16_f32 v61, v64, v0
	s_waitcnt lgkmcnt(0)
	v_mfma_f32_32x32x16_bf16 v[34:49], v[78:81], v[102:105], v[34:49]
	v_mfma_f32_32x32x16_bf16 v[66:81], v[66:69], v[70:73], 0
	s_nop 10
	v_cndmask_b32_e64 v34, v34, 0, s[62:63]
	v_cndmask_b32_e64 v35, 0, v35, s[0:1]
	v_cvt_pk_bf16_f32 v34, v34, v35
	v_cndmask_b32_e64 v42, v42, 0, s[76:77]
	v_cndmask_b32_e64 v43, v43, 0, s[78:79]
	v_cvt_pk_bf16_f32 v42, v42, v43
	v_cndmask_b32_e64 v43, v44, 0, s[80:81]
	v_mfma_f32_32x32x16_bf16 v[66:81], v[82:85], v[94:97], v[66:81]
	v_cndmask_b32_e64 v82, 0, v55, s[40:41]
	v_cndmask_b32_e64 v83, 0, v56, s[42:43]
	v_cvt_pk_bf16_f32 v55, v51, v52
	v_cvt_pk_bf16_f32 v56, v53, v82
	v_cvt_pk_bf16_f32 v57, v83, v57
	ds_read_b64_tr_b16 v[146:147], v157 offset:0x4000
	ds_read_b64_tr_b16 v[148:149], v157 offset:0x4000+1024
	ds_read_b64_tr_b16 v[134:135], v157 offset:0x4000+2048
	ds_read_b64_tr_b16 v[136:137], v157 offset:0x4000+3072
	ds_read_b64_tr_b16 v[126:127], v176 offset:0x1000
	ds_read_b64_tr_b16 v[128:129], v176 offset:0x1000+1024
	ds_read_b64_tr_b16 v[122:123], v176 offset:0x1000+2048
	ds_read_b64_tr_b16 v[124:125], v176 offset:0x1000+3072
	ds_read_b64_tr_b16 v[118:119], v176 offset:0x1000+64
	ds_read_b64_tr_b16 v[120:121], v176 offset:0x1000+64+1024
	ds_read_b64_tr_b16 v[114:115], v176 offset:0x1000+64+2048
	ds_read_b64_tr_b16 v[116:117], v176 offset:0x1000+64+3072
	ds_read_b64_tr_b16 v[50:51], v176 offset:0x2000
	ds_read_b64_tr_b16 v[52:53], v176 offset:0x2000+1024
	ds_read_b64_tr_b16 v[138:139], v176 offset:0x2000+2048
	ds_read_b64_tr_b16 v[140:141], v176 offset:0x2000+3072
	ds_read_b64_tr_b16 v[142:143], v176 offset:0x2000+64
	ds_read_b64_tr_b16 v[144:145], v176 offset:0x2000+64+1024
	ds_read_b64_tr_b16 v[130:131], v176 offset:0x2000+64+2048
	ds_read_b64_tr_b16 v[132:133], v176 offset:0x2000+64+3072
	s_waitcnt lgkmcnt(0)
	ds_read2_b64 v[242:245], v106 offset0:4 offset1:6
	v_mfma_f32_32x32x16_bf16 v[66:81], v[86:89], v[98:101], v[66:81]
	ds_read2_b64 v[98:101], v195 offset0:8 offset1:10
	v_cndmask_b32_e64 v44, v45, 0, s[82:83]
	v_cvt_pk_bf16_f32 v43, v43, v44
	v_cndmask_b32_e64 v44, v46, 0, s[84:85]
	v_mfma_f32_32x32x16_bf16 v[66:81], v[90:93], v[102:105], v[66:81]
	ds_read2_b64 v[102:105], v195 offset0:12 offset1:14
	v_mfma_f32_32x32x16_bf16 v[82:97], v[54:57], v[146:149], 0
	ds_read2_b64 v[54:57], v195 offset1:2
	s_nop 8
	v_cndmask_b32_e64 v0, v66, 0, s[62:63]
	v_cndmask_b32_e64 v62, 0, v67, s[0:1]
	v_cndmask_b32_e64 v63, v68, 0, s[64:65]
	v_cndmask_b32_e64 v64, v69, 0, s[66:67]
	v_cndmask_b32_e64 v65, v70, 0, s[68:69]
	v_cndmask_b32_e64 v66, v71, 0, s[70:71]
	v_mfma_f32_32x32x16_bf16 v[82:97], v[58:61], v[134:137], v[82:97]
	ds_read2_b64 v[58:61], v195 offset0:4 offset1:6
	v_cndmask_b32_e64 v67, v73, 0, s[74:75]
	v_cndmask_b32_e64 v213, v75, 0, s[78:79]
	v_cndmask_b32_e64 v218, v76, 0, s[80:81]
	v_cndmask_b32_e64 v219, v77, 0, s[82:83]
	v_cvt_pk_bf16_f32 v75, v12, v13
	v_cvt_pk_bf16_f32 v76, v14, v15
	s_waitcnt lgkmcnt(1)
	v_mfma_f32_32x32x16_bf16 v[82:97], v[54:57], v[214:217], v[82:97]
	v_cndmask_b32_e64 v57, v72, 0, s[72:73]
	v_cvt_pk_bf16_f32 v54, v0, v62
	v_cvt_pk_bf16_f32 v55, v63, v64
	v_cvt_pk_bf16_f32 v56, v65, v66
	v_cvt_pk_bf16_f32 v57, v57, v67
	v_cndmask_b32_e64 v0, v74, 0, s[76:77]
	v_cvt_pk_bf16_f32 v74, v10, v11
	s_waitcnt lgkmcnt(0)
	v_mfma_f32_32x32x16_bf16 v[82:97], v[58:61], v[228:231], v[82:97]
	v_cvt_pk_bf16_f32 v77, v16, v17
	v_cndmask_b32_e64 v237, v78, 0, s[84:85]
	v_cndmask_b32_e64 v246, v79, 0, s[86:87]
	v_cvt_pk_bf16_f32 v78, v0, v213
	v_cvt_pk_bf16_f32 v79, v218, v219
	v_add_u32_e32 v0, 0x3000, v195
	v_mfma_f32_32x32x16_bf16 v[58:73], v[54:57], v[146:149], 0
	v_cvt_pk_bf16_f32 v54, v2, v3
	v_cvt_pk_bf16_f32 v55, v4, v5
	v_cvt_pk_bf16_f32 v56, v6, v7
	v_cvt_pk_bf16_f32 v57, v8, v9
	s_nop 1
	v_mfma_f32_32x32x16_bf16 v[82:97], v[98:101], v[54:57], v[82:97]
	ds_read2_b64 v[98:101], v106 offset1:2
	v_mfma_f32_32x32x16_bf16 v[82:97], v[102:105], v[74:77], v[82:97]
	s_nop 11
	v_cvt_pk_bf16_f32 v82, v82, v83
	v_cvt_pk_bf16_f32 v83, v84, v85
	v_cvt_pk_bf16_f32 v84, v86, v87
	v_cvt_pk_bf16_f32 v85, v88, v89
	s_waitcnt lgkmcnt(0)
	s_nop 0
	v_mfma_f32_32x32x16_bf16 v[98:113], v[98:101], v[82:85], 0
	v_cndmask_b32_e64 v84, v80, 0, s[88:89]
	v_cndmask_b32_e64 v85, v81, 0, s[90:91]
	v_cvt_pk_bf16_f32 v80, v90, v91
	v_cvt_pk_bf16_f32 v81, v92, v93
	v_cvt_pk_bf16_f32 v82, v94, v95
	v_cvt_pk_bf16_f32 v83, v96, v97
	ds_read2_b64 v[90:93], v0 offset0:4 offset1:6
	s_nop 0
	v_mfma_f32_32x32x16_bf16 v[98:113], v[242:245], v[80:83], v[98:113]
	v_cvt_pk_bf16_f32 v80, v237, v246
	v_cvt_pk_bf16_f32 v81, v84, v85
	ds_read2_b64 v[82:85], v0 offset1:2
	s_nop 0
	v_mfma_f32_32x32x16_bf16 v[58:73], v[78:81], v[134:137], v[58:73]
	s_nop 6
	v_cvt_pk_bf16_f32 v86, v98, v99
	v_cvt_pk_bf16_f32 v87, v100, v101
	v_cvt_pk_bf16_f32 v88, v102, v103
	v_cvt_pk_bf16_f32 v89, v104, v105
	v_cvt_pk_bf16_f32 v78, v106, v107
	v_cvt_pk_bf16_f32 v79, v108, v109
	v_cvt_pk_bf16_f32 v80, v110, v111
	s_waitcnt lgkmcnt(0)
	v_mfma_f32_32x32x16_bf16 v[58:73], v[82:85], v[214:217], v[58:73]
	ds_read2_b64 v[82:85], v0 offset0:8 offset1:10
	v_cvt_pk_bf16_f32 v81, v112, v113
	v_mfma_f32_32x32x16_bf16 v[58:73], v[90:93], v[228:231], v[58:73]
	ds_read2_b64 v[90:93], v0 offset0:12 offset1:14
	v_cndmask_b32_e64 v0, v36, 0, s[64:65]
	v_cndmask_b32_e64 v36, v37, 0, s[66:67]
	v_cndmask_b32_e64 v37, v38, 0, s[68:69]
	v_cndmask_b32_e64 v38, v39, 0, s[70:71]
	v_cndmask_b32_e64 v39, v40, 0, s[72:73]
	v_cndmask_b32_e64 v40, v41, 0, s[74:75]
	s_waitcnt lgkmcnt(1)
	v_mfma_f32_32x32x16_bf16 v[58:73], v[82:85], v[54:57], v[58:73]
	v_cvt_pk_bf16_f32 v35, v0, v36
	v_cvt_pk_bf16_f32 v36, v37, v38
	v_cvt_pk_bf16_f32 v37, v39, v40
	v_cndmask_b32_e64 v0, v47, 0, s[86:87]
	v_cvt_pk_bf16_f32 v44, v44, v0
	v_cndmask_b32_e64 v0, v48, 0, s[88:89]
	v_cndmask_b32_e64 v38, v49, 0, s[90:91]
	s_waitcnt lgkmcnt(0)
	v_mfma_f32_32x32x16_bf16 v[58:73], v[90:93], v[74:77], v[58:73]
	v_cvt_pk_bf16_f32 v45, v0, v38
	v_mfma_f32_32x32x16_bf16 v[58:73], v[34:37], v[86:89], v[58:73]
	v_add_u32_e32 v34, s8, v155
	v_ashrrev_i32_e32 v35, 31, v34
	v_lshlrev_b64 v[34:35], 12, v[34:35]
	v_lshl_add_u64 v[34:35], v[158:159], 0, v[34:35]
	v_mfma_f32_32x32x16_bf16 v[58:73], v[42:45], v[78:81], v[58:73]
	v_mfma_f32_32x32x16_bf16 v[18:33], v[126:129], v[86:89], v[18:33]
	s_nop 10
	global_store_dword v[34:35], v58, off
	v_add_u32_e32 v34, s8, v197
	v_ashrrev_i32_e32 v35, 31, v34
	v_lshlrev_b64 v[34:35], 12, v[34:35]
	v_lshl_add_u64 v[34:35], v[158:159], 0, v[34:35]
	global_store_dword v[34:35], v59, off
	v_add_u32_e32 v34, s8, v198
	v_ashrrev_i32_e32 v35, 31, v34
	v_lshlrev_b64 v[34:35], 12, v[34:35]
	v_lshl_add_u64 v[34:35], v[158:159], 0, v[34:35]
	global_store_dword v[34:35], v60, off
	v_add_u32_e32 v34, s8, v199
	v_ashrrev_i32_e32 v35, 31, v34
	v_lshlrev_b64 v[34:35], 12, v[34:35]
	v_lshl_add_u64 v[34:35], v[158:159], 0, v[34:35]
	global_store_dword v[34:35], v61, off
	v_add_u32_e32 v34, s8, v200
	v_ashrrev_i32_e32 v35, 31, v34
	v_lshlrev_b64 v[34:35], 12, v[34:35]
	v_lshl_add_u64 v[34:35], v[158:159], 0, v[34:35]
	global_store_dword v[34:35], v62, off
	v_add_u32_e32 v34, s8, v201
	v_ashrrev_i32_e32 v35, 31, v34
	v_lshlrev_b64 v[34:35], 12, v[34:35]
	v_lshl_add_u64 v[34:35], v[158:159], 0, v[34:35]
	global_store_dword v[34:35], v63, off
	v_add_u32_e32 v34, s8, v202
	v_ashrrev_i32_e32 v35, 31, v34
	v_lshlrev_b64 v[34:35], 12, v[34:35]
	v_lshl_add_u64 v[34:35], v[158:159], 0, v[34:35]
	global_store_dword v[34:35], v64, off
	v_add_u32_e32 v34, s8, v203
	v_ashrrev_i32_e32 v35, 31, v34
	v_lshlrev_b64 v[34:35], 12, v[34:35]
	v_lshl_add_u64 v[34:35], v[158:159], 0, v[34:35]
	global_store_dword v[34:35], v65, off
	v_add_u32_e32 v34, s8, v204
	v_ashrrev_i32_e32 v35, 31, v34
	v_lshlrev_b64 v[34:35], 12, v[34:35]
	v_lshl_add_u64 v[34:35], v[158:159], 0, v[34:35]
	global_store_dword v[34:35], v66, off
	v_add_u32_e32 v34, s8, v205
	v_ashrrev_i32_e32 v35, 31, v34
	v_lshlrev_b64 v[34:35], 12, v[34:35]
	v_lshl_add_u64 v[34:35], v[158:159], 0, v[34:35]
	v_add_u32_e32 v66, s8, v206
	global_store_dword v[34:35], v67, off
	v_ashrrev_i32_e32 v67, 31, v66
	v_lshlrev_b64 v[66:67], 12, v[66:67]
	v_lshl_add_u64 v[66:67], v[158:159], 0, v[66:67]
	global_store_dword v[66:67], v68, off
	v_add_u32_e32 v66, s8, v207
	v_ashrrev_i32_e32 v67, 31, v66
	v_lshlrev_b64 v[66:67], 12, v[66:67]
	v_lshl_add_u64 v[66:67], v[158:159], 0, v[66:67]
	global_store_dword v[66:67], v69, off
	v_add_u32_e32 v66, s8, v208
	v_ashrrev_i32_e32 v67, 31, v66
	v_lshlrev_b64 v[66:67], 12, v[66:67]
	v_lshl_add_u64 v[66:67], v[158:159], 0, v[66:67]
	global_store_dword v[66:67], v70, off
	v_add_u32_e32 v66, s8, v209
	v_ashrrev_i32_e32 v67, 31, v66
	v_lshlrev_b64 v[66:67], 12, v[66:67]
	v_lshl_add_u64 v[66:67], v[158:159], 0, v[66:67]
	global_store_dword v[66:67], v71, off
	v_add_u32_e32 v66, s8, v210
	v_mfma_f32_32x32x16_bf16 v[34:49], v[142:145], v[146:149], 0
	v_ashrrev_i32_e32 v67, 31, v66
	v_lshlrev_b64 v[66:67], 12, v[66:67]
	v_lshl_add_u64 v[66:67], v[158:159], 0, v[66:67]
	global_store_dword v[66:67], v72, off
	v_add_u32_e32 v66, s8, v211
	v_ashrrev_i32_e32 v67, 31, v66
	v_lshlrev_b64 v[66:67], 12, v[66:67]
	v_mfma_f32_32x32x16_bf16 v[50:65], v[50:53], v[146:149], 0
	v_lshl_add_u64 v[66:67], v[158:159], 0, v[66:67]
	global_store_dword v[66:67], v73, off
	v_add_u32_e32 v144, s22, v160
	s_cselect_b64 s[8:9], -1, 0
	s_and_b64 vcc, exec, s[8:9]
	v_mfma_f32_32x32x16_bf16 v[2:17], v[118:121], v[86:89], v[2:17]
	v_mfma_f32_32x32x16_bf16 v[34:49], v[130:133], v[134:137], v[34:49]
	v_mfma_f32_32x32x16_bf16 v[18:33], v[122:125], v[78:81], v[18:33]
	ds_read_b128 v[130:133], v144 offset:22528
	ds_read_b128 v[126:129], v144 offset:22560
	ds_read_b128 v[122:125], v144 offset:22592
	ds_read_b128 v[108:111], v144 offset:22624
	ds_read_b128 v[100:103], v144 offset:22656
	ds_read_b128 v[96:99], v144 offset:22688
	ds_read_b128 v[104:107], v144 offset:22720
	ds_read_b128 v[92:95], v144 offset:22752
	v_mov_b32_e32 v250, s101
	v_mov_b32_e32 v251, s100
	ds_write_b32 v250, v251
	s_mov_b32 s4, 0
	v_mov_b32_e32 v250, 0x20800
